# attention pair->XCD remap + SGU loads issued up front
# speedup vs baseline: 1.0041x; 1.0041x over previous
; #define LAS __attribute__((address_space(3)))
; __device__ __forceinline__ unsigned cvt_pk_bf16(float lo, float hi) { unsigned r; asm volatile("v_cvt_pk_bf16_f32 %0, %1, %2" : "=v"(r) : "v"(lo), "v"(hi)); return r; }
; __device__ __forceinline__ float bf_lo(unsigned w) { return __uint_as_float(w << 16); }
; __device__ __forceinline__ float bf_hi(unsigned w) { return __uint_as_float(w & 0xffff0000u); }
; __device__ __forceinline__ void sgu_phase(LAS unsigned char* lds, const bf16_t* U, const bf16_t* GV, const bf16_t* SZ, const float* stats, const float* vg, const float* vb,
;                                           const bf16_t* wsb, const float* b_s, bf16_t* Y, int G, int bid) {
;     ...
; #pragma unroll
;         for (int i = 0; i < 4; ++i) {
;             const int id = tid + 512 * i, r = id >> 4, cc = id & 15;
;             const u32x4 w = *(const u32x4*)(GV + (size_t)(row0 + r) * DM + g * 128 + cc * 8);
;             const f32x2 st = rstat[r];
;             const f32x4 g0 = *(const f32x4*)(vg + g * 128 + cc * 8), g1 = *(const f32x4*)(vg + g * 128 + cc * 8 + 4);
;             const f32x4 b0 = *(const f32x4*)(vb + g * 128 + cc * 8), b1 = *(const f32x4*)(vb + g * 128 + cc * 8 + 4);
;             float f[8] = {bf_lo(w.x), bf_hi(w.x), bf_lo(w.y), bf_hi(w.y), bf_lo(w.z), bf_hi(w.z), bf_lo(w.w), bf_hi(w.w)};
; #pragma unroll
;             for (int j = 0; j < 8; ++j) {
;                 const float gg = j < 4 ? g0[j & 3] : g1[j & 3], bb = j < 4 ? b0[j & 3] : b1[j & 3];
;                 const float vn = (f[j] - st.x) * st.y * gg + bb;
;                 *(LAS bf16_t*)(vnT + (cc * 8 + j) * VST + (((r >> 3) ^ cc) << 4) + (r & 7) * 2) = (bf16_t)(cvt_pk_bf16(vn, 0.f) & 0xffffu);
;             }
;         }
;     ...
;         const int t = wid * 16 + fr; const float bs = b_s[g * 128 + t];
;         const size_t ro = (size_t)(row0 + t) * DM + g * 128 + 4 * fq;
; #pragma unroll
;         for (int ct = 0; ct < 8; ++ct) {
;             const u32x2 uw = *(const u32x2*)(U + ro + ct * 16);
.LBB0_237:
	s_or_b64 exec, exec, s[24:25]
	s_lshl_b32 s0, s18, 7
	s_and_b32 s36, s0, 0x780
	v_or_b32_e32 v0, s27, v214
	s_lshl_b32 s18, s36, 1
	v_ashrrev_i32_e32 v1, 31, v0
	v_lshl_add_u64 v[4:5], v[34:35], 0, s[18:19]
	v_lshlrev_b64 v[0:1], 12, v[0:1]
	v_lshl_add_u64 v[0:1], v[4:5], 0, v[0:1]
	v_add_u32_e32 v240, s27, v47
	v_ashrrev_i32_e32 v241, 31, v240
	v_lshlrev_b64 v[240:241], 11, v[240:241]
	v_or3_b32 v240, v240, v40, s36
	v_lshlrev_b64 v[240:241], 1, v[240:241]
	v_lshl_add_u64 v[240:241], s[8:9], 0, v[240:241]
	v_add_lshl_u32 v242, s36, v47, 2
	global_load_dword v126, v242, s[28:29]
	global_load_dwordx2 v[110:111], v[240:241], off
	global_load_dwordx2 v[112:113], v[240:241], off offset:32
	global_load_dwordx2 v[114:115], v[240:241], off offset:64
	global_load_dwordx2 v[116:117], v[240:241], off offset:96
	global_load_dwordx2 v[118:119], v[240:241], off offset:128
	global_load_dwordx2 v[120:121], v[240:241], off offset:160
	global_load_dwordx2 v[122:123], v[240:241], off offset:192
	global_load_dwordx2 v[124:125], v[240:241], off offset:224
	s_waitcnt lgkmcnt(0)
	s_barrier
	global_load_dwordx4 v[6:9], v[0:1], off
	s_lshl_b32 s18, s36, 2
	v_lshl_add_u64 v[2:3], v[38:39], 0, s[18:19]
	v_lshl_add_u64 v[0:1], v[36:37], 0, s[18:19]
	global_load_dwordx4 v[10:13], v[2:3], off
	global_load_dwordx4 v[14:17], v[0:1], off
	global_load_dwordx4 v[18:21], v[0:1], off offset:16
	global_load_dwordx4 v[22:25], v[2:3], off offset:16
	ds_read_b64 v[26:27], v49 offset:34816
	v_or_b32_e32 v28, s27, v50
	v_ashrrev_i32_e32 v29, 31, v28
	v_lshlrev_b64 v[28:29], 12, v[28:29]
	v_lshl_add_u64 v[28:29], v[4:5], 0, v[28:29]
	s_mov_b64 s[24:25], 0
	v_mov_b32_e32 v69, v41
	v_mov_b32_e32 v70, v64
	global_load_dwordx4 v[170:173], v[28:29], off
	global_load_dwordx4 v[174:177], v[2:3], off
	global_load_dwordx4 v[178:181], v[0:1], off
	global_load_dwordx4 v[182:185], v[0:1], off offset:16
	global_load_dwordx4 v[186:189], v[2:3], off offset:16
	v_or_b32_e32 v236, s27, v52
	v_ashrrev_i32_e32 v237, 31, v236
	v_lshlrev_b64 v[236:237], 12, v[236:237]
	v_lshl_add_u64 v[236:237], v[4:5], 0, v[236:237]
	global_load_dwordx4 v[190:193], v[236:237], off
	global_load_dwordx4 v[194:197], v[2:3], off
	global_load_dwordx4 v[198:201], v[0:1], off
	global_load_dwordx4 v[202:205], v[0:1], off offset:16
	global_load_dwordx4 v[206:209], v[2:3], off offset:16
	v_add_u32_e32 v238, s27, v54
	v_ashrrev_i32_e32 v239, 31, v238
	v_lshlrev_b64 v[238:239], 12, v[238:239]
	v_lshl_add_u64 v[238:239], v[4:5], 0, v[238:239]
	global_load_dwordx4 v[72:75], v[238:239], off
	global_load_dwordx4 v[76:79], v[2:3], off
	global_load_dwordx4 v[80:83], v[0:1], off
	global_load_dwordx4 v[84:87], v[0:1], off offset:16
	global_load_dwordx4 v[88:91], v[2:3], off offset:16
	s_waitcnt vmcnt(19)
	v_lshlrev_b32_e32 v30, 16, v6
	v_and_b32_e32 v6, 0xffff0000, v6
	v_lshlrev_b32_e32 v44, 16, v9
	v_and_b32_e32 v9, 0xffff0000, v9
	s_waitcnt lgkmcnt(0)
	v_sub_f32_e32 v6, v6, v26
	v_lshlrev_b32_e32 v31, 16, v7
	v_and_b32_e32 v7, 0xffff0000, v7
	v_lshlrev_b32_e32 v32, 16, v8
	v_and_b32_e32 v8, 0xffff0000, v8
	v_sub_f32_e32 v30, v30, v26
	v_sub_f32_e32 v9, v9, v26
	v_mul_f32_e32 v6, v27, v6
	v_sub_f32_e32 v31, v31, v26
	v_sub_f32_e32 v7, v7, v26
	v_sub_f32_e32 v32, v32, v26
	v_sub_f32_e32 v8, v8, v26
	v_sub_f32_e32 v44, v44, v26
	v_mul_f32_e32 v26, v27, v30
	v_mul_f32_e32 v9, v27, v9
	s_waitcnt vmcnt(17)
	v_fma_f32 v6, v15, v6, v11
	v_mul_f32_e32 v30, v27, v31
	v_fma_f32 v10, v14, v26, v10
	s_waitcnt vmcnt(15)
	v_fmac_f32_e32 v25, v21, v9
	v_cvt_pk_bf16_f32 v9, v10, v33
	ds_write_b16 v65, v9
	v_cvt_pk_bf16_f32 v6, v6, v33
	v_mul_f32_e32 v7, v27, v7
	v_fma_f32 v11, v16, v30, v12
	ds_write_b16 v65, v6 offset:272
	v_cvt_pk_bf16_f32 v6, v11, v33
	v_mul_f32_e32 v31, v27, v32
	v_fmac_f32_e32 v13, v17, v7
	ds_write_b16 v65, v6 offset:544
	v_cvt_pk_bf16_f32 v6, v13, v33
	v_mul_f32_e32 v8, v27, v8
	v_fma_f32 v7, v18, v31, v22
	ds_write_b16 v65, v6 offset:816
	v_cvt_pk_bf16_f32 v6, v7, v33
	v_mul_f32_e32 v32, v27, v44
	v_fma_f32 v8, v19, v8, v23
	ds_write_b16 v65, v6 offset:1088
	v_cvt_pk_bf16_f32 v6, v8, v33
	v_fma_f32 v12, v20, v32, v24
	ds_write_b16 v65, v6 offset:1360
	v_cvt_pk_bf16_f32 v6, v12, v33
	ds_write_b16 v65, v6 offset:1632
	v_cvt_pk_bf16_f32 v30, v25, v33
	ds_write_b16 v65, v30 offset:1904
	ds_read_b64 v[28:29], v51 offset:34816
	v_or_b32_e32 v26, s27, v52
	v_ashrrev_i32_e32 v27, 31, v26
	v_lshlrev_b64 v[26:27], 12, v[26:27]
	v_lshl_add_u64 v[26:27], v[4:5], 0, v[26:27]
	s_waitcnt vmcnt(14)
	v_lshlrev_b32_e32 v30, 16, v170
	v_and_b32_e32 v170, 0xffff0000, v170
	v_lshlrev_b32_e32 v44, 16, v173
	v_and_b32_e32 v173, 0xffff0000, v173
	s_waitcnt lgkmcnt(0)
	v_sub_f32_e32 v170, v170, v28
	v_lshlrev_b32_e32 v31, 16, v171
	v_and_b32_e32 v171, 0xffff0000, v171
	v_lshlrev_b32_e32 v32, 16, v172
	v_and_b32_e32 v172, 0xffff0000, v172
	v_sub_f32_e32 v30, v30, v28
	v_sub_f32_e32 v173, v173, v28
	v_mul_f32_e32 v170, v29, v170
	v_sub_f32_e32 v31, v31, v28
	v_sub_f32_e32 v171, v171, v28
	v_sub_f32_e32 v32, v32, v28
	v_sub_f32_e32 v172, v172, v28
	v_sub_f32_e32 v44, v44, v28
	v_mul_f32_e32 v28, v29, v30
	v_mul_f32_e32 v173, v29, v173
	s_waitcnt vmcnt(12)
	v_fma_f32 v170, v179, v170, v175
	v_mul_f32_e32 v30, v29, v31
	v_fma_f32 v174, v178, v28, v174
	s_waitcnt vmcnt(10)
; #define LAS __attribute__((address_space(3)))
; __device__ __forceinline__ unsigned cvt_pk_bf16(float lo, float hi) { unsigned r; asm volatile("v_cvt_pk_bf16_f32 %0, %1, %2" : "=v"(r) : "v"(lo), "v"(hi)); return r; }
; __device__ __forceinline__ float bf_lo(unsigned w) { return __uint_as_float(w << 16); }
; __device__ __forceinline__ float bf_hi(unsigned w) { return __uint_as_float(w & 0xffff0000u); }
; __device__ __forceinline__ void sgu_phase(LAS unsigned char* lds, const bf16_t* U, const bf16_t* GV, const bf16_t* SZ, const float* stats, const float* vg, const float* vb,
;                                           const bf16_t* wsb, const float* b_s, bf16_t* Y, int G, int bid) {
;     ...
; #pragma unroll
;         for (int i = 0; i < 4; ++i) {
;             const int id = tid + 512 * i, r = id >> 4, cc = id & 15;
;             const u32x4 w = *(const u32x4*)(GV + (size_t)(row0 + r) * DM + g * 128 + cc * 8);
;             const f32x2 st = rstat[r];
;             const f32x4 g0 = *(const f32x4*)(vg + g * 128 + cc * 8), g1 = *(const f32x4*)(vg + g * 128 + cc * 8 + 4);
;             const f32x4 b0 = *(const f32x4*)(vb + g * 128 + cc * 8), b1 = *(const f32x4*)(vb + g * 128 + cc * 8 + 4);
;             float f[8] = {bf_lo(w.x), bf_hi(w.x), bf_lo(w.y), bf_hi(w.y), bf_lo(w.z), bf_hi(w.z), bf_lo(w.w), bf_hi(w.w)};
; #pragma unroll
;             for (int j = 0; j < 8; ++j) {
;                 const float gg = j < 4 ? g0[j & 3] : g1[j & 3], bb = j < 4 ? b0[j & 3] : b1[j & 3];
;                 const float vn = (f[j] - st.x) * st.y * gg + bb;
;                 *(LAS bf16_t*)(vnT + (cc * 8 + j) * VST + (((r >> 3) ^ cc) << 4) + (r & 7) * 2) = (bf16_t)(cvt_pk_bf16(vn, 0.f) & 0xffffu);
;             }
;         }
;         __syncthreads();
;         f32x4 acc[8];
; #pragma unroll
;         for (int ct = 0; ct < 8; ++ct) acc[ct] = (f32x4){0.f, 0.f, 0.f, 0.f};
	v_fmac_f32_e32 v189, v185, v173
	v_cvt_pk_bf16_f32 v173, v174, v33
	ds_write_b16 v66, v173
	v_cvt_pk_bf16_f32 v170, v170, v33
	v_mul_f32_e32 v171, v29, v171
	v_fma_f32 v175, v180, v30, v176
	ds_write_b16 v66, v170 offset:272
	v_cvt_pk_bf16_f32 v170, v175, v33
	v_mul_f32_e32 v31, v29, v32
	v_fmac_f32_e32 v177, v181, v171
	ds_write_b16 v66, v170 offset:544
	v_cvt_pk_bf16_f32 v170, v177, v33
	v_mul_f32_e32 v172, v29, v172
	v_fma_f32 v171, v182, v31, v186
	ds_write_b16 v66, v170 offset:816
	v_cvt_pk_bf16_f32 v170, v171, v33
	v_mul_f32_e32 v32, v29, v44
	v_fma_f32 v172, v183, v172, v187
	ds_write_b16 v66, v170 offset:1088
	v_cvt_pk_bf16_f32 v170, v172, v33
	v_fma_f32 v176, v184, v32, v188
	ds_write_b16 v66, v170 offset:1360
	v_cvt_pk_bf16_f32 v170, v176, v33
	ds_write_b16 v66, v170 offset:1632
	v_cvt_pk_bf16_f32 v28, v189, v33
	v_add_u32_e32 v26, s27, v54
	v_ashrrev_i32_e32 v27, 31, v26
	v_lshlrev_b64 v[26:27], 12, v[26:27]
	ds_write_b16 v66, v28 offset:1904
	v_lshl_add_u64 v[4:5], v[4:5], 0, v[26:27]
	ds_read_b64 v[26:27], v53 offset:34816
	v_add_lshl_u32 v32, v47, s36, 8
	v_lshl_add_u64 v[44:45], v[42:43], 0, v[32:33]
	s_waitcnt vmcnt(9)
	v_lshlrev_b32_e32 v28, 16, v190
	v_and_b32_e32 v190, 0xffff0000, v190
	v_lshlrev_b32_e32 v31, 16, v193
	v_and_b32_e32 v193, 0xffff0000, v193
	s_waitcnt lgkmcnt(0)
	v_sub_f32_e32 v190, v190, v26
	v_lshlrev_b32_e32 v29, 16, v191
	v_and_b32_e32 v191, 0xffff0000, v191
	v_lshlrev_b32_e32 v30, 16, v192
	v_and_b32_e32 v192, 0xffff0000, v192
	v_sub_f32_e32 v28, v28, v26
	v_sub_f32_e32 v193, v193, v26
	v_mul_f32_e32 v190, v27, v190
	v_sub_f32_e32 v29, v29, v26
	v_sub_f32_e32 v191, v191, v26
	v_sub_f32_e32 v30, v30, v26
	v_sub_f32_e32 v192, v192, v26
	v_sub_f32_e32 v31, v31, v26
	v_mul_f32_e32 v26, v27, v28
	v_mul_f32_e32 v193, v27, v193
	s_waitcnt vmcnt(7)
	v_fma_f32 v190, v199, v190, v195
	v_mul_f32_e32 v28, v27, v29
	v_fma_f32 v194, v198, v26, v194
	s_waitcnt vmcnt(5)
	v_fmac_f32_e32 v209, v205, v193
	v_cvt_pk_bf16_f32 v193, v194, v33
	ds_write_b16 v67, v193
	v_cvt_pk_bf16_f32 v190, v190, v33
	v_mul_f32_e32 v191, v27, v191
	v_fma_f32 v195, v200, v28, v196
	ds_write_b16 v67, v190 offset:272
	v_cvt_pk_bf16_f32 v190, v195, v33
	v_mul_f32_e32 v29, v27, v30
	v_fmac_f32_e32 v197, v201, v191
	ds_write_b16 v67, v190 offset:544
	v_cvt_pk_bf16_f32 v190, v197, v33
	v_mul_f32_e32 v192, v27, v192
	v_fma_f32 v191, v202, v29, v206
	ds_write_b16 v67, v190 offset:816
	v_cvt_pk_bf16_f32 v190, v191, v33
	v_mul_f32_e32 v30, v27, v31
	v_fma_f32 v192, v203, v192, v207
	ds_write_b16 v67, v190 offset:1088
	v_cvt_pk_bf16_f32 v190, v192, v33
	v_fma_f32 v196, v204, v30, v208
	ds_write_b16 v67, v190 offset:1360
	v_cvt_pk_bf16_f32 v190, v196, v33
	ds_write_b16 v67, v190 offset:1632
	v_cvt_pk_bf16_f32 v31, v209, v33
	ds_write_b16 v67, v31 offset:1904
	ds_read_b64 v[92:93], v55 offset:34816
	v_mov_b32_e32 v0, 0
	v_mov_b32_e32 v1, v0
	v_mov_b32_e32 v2, v0
	v_mov_b32_e32 v3, v0
	v_mov_b32_e32 v4, v0
	v_mov_b32_e32 v5, v0
	v_mov_b32_e32 v6, v0
	v_mov_b32_e32 v7, v0
	v_mov_b32_e32 v8, v0
	v_mov_b32_e32 v9, v0
	v_mov_b32_e32 v10, v0
	v_mov_b32_e32 v11, v0
	v_mov_b32_e32 v12, v0
	v_mov_b32_e32 v13, v0
	v_mov_b32_e32 v14, v0
	v_mov_b32_e32 v15, v0
	v_mov_b32_e32 v16, v0
	v_mov_b32_e32 v17, v0
	v_mov_b32_e32 v18, v0
	v_mov_b32_e32 v19, v0
	v_mov_b32_e32 v20, v0
	v_mov_b32_e32 v21, v0
	v_mov_b32_e32 v22, v0
	v_mov_b32_e32 v23, v0
	v_mov_b32_e32 v24, v0
	v_mov_b32_e32 v25, v0
	v_mov_b32_e32 v26, v0
	v_mov_b32_e32 v27, v0
	v_mov_b32_e32 v28, v0
	v_mov_b32_e32 v29, v0
	v_mov_b32_e32 v30, v0
	s_waitcnt vmcnt(4)
	v_lshlrev_b32_e32 v31, 16, v72
	s_waitcnt lgkmcnt(0)
	v_sub_f32_e32 v31, v31, v92
	v_and_b32_e32 v32, 0xffff0000, v72
	v_mul_f32_e32 v31, v93, v31
	v_lshlrev_b32_e32 v71, 16, v73
	v_sub_f32_e32 v32, v32, v92
	s_waitcnt vmcnt(2)
	v_fma_f32 v31, v80, v31, v76
	v_and_b32_e32 v72, 0xffff0000, v73
	v_sub_f32_e32 v71, v71, v92
	v_mul_f32_e32 v32, v93, v32
	v_cvt_pk_bf16_f32 v31, v31, v33
	v_lshlrev_b32_e32 v73, 16, v74
	v_sub_f32_e32 v72, v72, v92
	v_mul_f32_e32 v71, v93, v71
	v_fma_f32 v32, v81, v32, v77
	ds_write_b16 v68, v31
	v_cvt_pk_bf16_f32 v31, v32, v33
	v_and_b32_e32 v74, 0xffff0000, v74
	v_sub_f32_e32 v73, v73, v92
	v_mul_f32_e32 v72, v93, v72
	v_fma_f32 v71, v82, v71, v78
	ds_write_b16 v68, v31 offset:272
	v_cvt_pk_bf16_f32 v31, v71, v33
	v_lshlrev_b32_e32 v94, 16, v75
	v_sub_f32_e32 v74, v74, v92
	v_mul_f32_e32 v73, v93, v73
	v_fmac_f32_e32 v79, v83, v72
	ds_write_b16 v68, v31 offset:544
	v_cvt_pk_bf16_f32 v31, v79, v33
	v_and_b32_e32 v75, 0xffff0000, v75
	v_sub_f32_e32 v94, v94, v92
	v_mul_f32_e32 v74, v93, v74
	s_waitcnt vmcnt(0)
	v_fma_f32 v72, v84, v73, v88
	ds_write_b16 v68, v31 offset:816
	v_cvt_pk_bf16_f32 v31, v72, v33
	v_sub_f32_e32 v75, v75, v92
	v_mul_f32_e32 v92, v93, v94
	v_fma_f32 v73, v85, v74, v89
	ds_write_b16 v68, v31 offset:1088
	v_cvt_pk_bf16_f32 v31, v73, v33
	v_mul_f32_e32 v75, v93, v75
	v_fma_f32 v74, v86, v92, v90
	ds_write_b16 v68, v31 offset:1360
	v_cvt_pk_bf16_f32 v31, v74, v33
	v_fmac_f32_e32 v91, v87, v75
	ds_write_b16 v68, v31 offset:1632
	v_cvt_pk_bf16_f32 v31, v91, v33
	ds_write_b16 v68, v31 offset:1904
	v_mov_b32_e32 v31, v0
	s_waitcnt lgkmcnt(0)
	s_barrier
; #define LAS __attribute__((address_space(3)))
; __device__ __forceinline__ unsigned cvt_pk_bf16(float lo, float hi) { unsigned r; asm volatile("v_cvt_pk_bf16_f32 %0, %1, %2" : "=v"(r) : "v"(lo), "v"(hi)); return r; }
; __device__ __forceinline__ float bf_lo(unsigned w) { return __uint_as_float(w << 16); }
; __device__ __forceinline__ float bf_hi(unsigned w) { return __uint_as_float(w & 0xffff0000u); }
; __device__ __forceinline__ void sgu_phase(LAS unsigned char* lds, const bf16_t* U, const bf16_t* GV, const bf16_t* SZ, const float* stats, const float* vg, const float* vb,
;                                           const bf16_t* wsb, const float* b_s, bf16_t* Y, int G, int bid) {
;     ...
;         for (int ks = 0; ks < nks; ++ks) {
;             const bf16x8 wf = *(const bf16x8*)(wrow + ks * 32);
; #pragma unroll
;             for (int ct = 0; ct < 8; ++ct) {
;                 const bf16x8 vf = *(const LAS bf16x8*)(vnT + (ct * 16 + fr) * VST + (((ks * 4 + fq) ^ (ct * 2 + (fr >> 3))) << 4));
;                 acc[ct] = __builtin_amdgcn_mfma_f32_16x16x32_bf16(vf, wf, acc[ct], 0, 0, 0);
;             }
;         }
;         const int t = wid * 16 + fr; const float bs = b_s[g * 128 + t];
;         const size_t ro = (size_t)(row0 + t) * DM + g * 128 + 4 * fq;
; #pragma unroll
;         for (int ct = 0; ct < 8; ++ct) {
;             const u32x2 uw = *(const u32x2*)(U + ro + ct * 16);
;             const float y0 = bf_lo(uw.x) * (acc[ct][0] + bs), y1 = bf_hi(uw.x) * (acc[ct][1] + bs);
;             const float y2 = bf_lo(uw.y) * (acc[ct][2] + bs), y3 = bf_hi(uw.y) * (acc[ct][3] + bs);
;             u32x2 o; o.x = cvt_pk_bf16(y0, y1); o.y = cvt_pk_bf16(y2, y3);
;             *(u32x2*)(Y + ro + ct * 16) = o;
;         }
.LBB0_238:
	global_load_dwordx4 v[72:75], v[44:45], off
	v_xor_b32_e32 v32, v69, v48
	v_xor_b32_e32 v71, v69, v57
	v_xor_b32_e32 v76, v69, v58
	v_xor_b32_e32 v77, v69, v59
	v_xor_b32_e32 v78, v69, v60
	v_xor_b32_e32 v79, v69, v61
	v_xor_b32_e32 v80, v69, v62
	v_xor_b32_e32 v81, v69, v63
	v_lshl_add_u32 v32, v32, 4, v56
	v_lshl_add_u32 v71, v71, 4, v56
	v_lshl_add_u32 v84, v76, 4, v56
	v_lshl_add_u32 v85, v77, 4, v56
	v_lshl_add_u32 v86, v78, 4, v56
	v_lshl_add_u32 v87, v79, 4, v56
	v_lshl_add_u32 v88, v80, 4, v56
	v_lshl_add_u32 v89, v81, 4, v56
	ds_read_b128 v[76:79], v32
	ds_read_b128 v[80:83], v71 offset:4352
	v_add_u32_e32 v70, -1, v70
	v_cmp_eq_u32_e64 s[0:1], 0, v70
	v_add_u32_e32 v69, 4, v69
	s_or_b64 s[24:25], s[0:1], s[24:25]
	v_lshl_add_u64 v[44:45], v[44:45], 0, 64
	s_waitcnt vmcnt(0) lgkmcnt(1)
	v_mfma_f32_16x16x32_bf16 v[28:31], v[76:79], v[72:75], v[28:31]
	ds_read_b128 v[76:79], v84 offset:8704
	s_waitcnt lgkmcnt(1)
	v_mfma_f32_16x16x32_bf16 v[24:27], v[80:83], v[72:75], v[24:27]
	ds_read_b128 v[80:83], v85 offset:13056
	s_waitcnt lgkmcnt(1)
	v_mfma_f32_16x16x32_bf16 v[20:23], v[76:79], v[72:75], v[20:23]
	ds_read_b128 v[76:79], v86 offset:17408
	s_waitcnt lgkmcnt(1)
	v_mfma_f32_16x16x32_bf16 v[16:19], v[80:83], v[72:75], v[16:19]
	ds_read_b128 v[80:83], v87 offset:21760
	s_waitcnt lgkmcnt(1)
	v_mfma_f32_16x16x32_bf16 v[12:15], v[76:79], v[72:75], v[12:15]
	ds_read_b128 v[76:79], v88 offset:26112
	s_waitcnt lgkmcnt(1)
	v_mfma_f32_16x16x32_bf16 v[8:11], v[80:83], v[72:75], v[8:11]
	ds_read_b128 v[80:83], v89 offset:30464
	s_waitcnt lgkmcnt(1)
	v_mfma_f32_16x16x32_bf16 v[4:7], v[76:79], v[72:75], v[4:7]
	s_waitcnt lgkmcnt(0)
	v_mfma_f32_16x16x32_bf16 v[0:3], v[80:83], v[72:75], v[0:3]
	s_andn2_b64 exec, exec, s[24:25]
	s_cbranch_execnz .LBB0_238
	s_or_b64 exec, exec, s[24:25]
	v_add_u32_e32 v44, s27, v47
	v_ashrrev_i32_e32 v45, 31, v44
	v_lshlrev_b64 v[44:45], 11, v[44:45]
	v_or3_b32 v45, v45, 0, 0
	v_or3_b32 v44, v44, v40, s36
	v_lshlrev_b64 v[44:45], 1, v[44:45]
	v_add_lshl_u32 v32, s36, v47, 2
	v_lshl_add_u64 v[70:71], s[8:9], 0, v[44:45]
	v_lshl_add_u64 v[44:45], s[38:39], 0, v[44:45]
	v_mov_b32_e32 v72, v110
	v_mov_b32_e32 v73, v111
	s_add_i32 s26, s26, s34
	s_cmpk_gt_i32 s26, 0x3ff
	v_add_f32_e32 v28, v28, v126
	v_add_f32_e32 v29, v29, v126
	v_lshlrev_b32_e32 v69, 16, v72
	v_and_b32_e32 v72, 0xffff0000, v72
	v_add_f32_e32 v30, v30, v126
	v_add_f32_e32 v31, v31, v126
	v_lshlrev_b32_e32 v74, 16, v73
	v_and_b32_e32 v73, 0xffff0000, v73
	v_mul_f32_e32 v28, v28, v69
	v_mul_f32_e32 v29, v29, v72
	v_mul_f32_e32 v30, v30, v74
	v_mul_f32_e32 v31, v31, v73
	v_cvt_pk_bf16_f32 v28, v28, v29
	v_cvt_pk_bf16_f32 v29, v30, v31
	global_store_dwordx2 v[44:45], v[28:29], off
	v_mov_b32_e32 v28, v112
	v_mov_b32_e32 v29, v113
	v_add_f32_e32 v24, v24, v126
	v_add_f32_e32 v25, v25, v126
	v_add_f32_e32 v26, v26, v126
	v_add_f32_e32 v27, v27, v126
	v_add_f32_e32 v20, v20, v126
	v_add_f32_e32 v21, v21, v126
	v_add_f32_e32 v22, v22, v126
	v_add_f32_e32 v23, v23, v126
	v_add_f32_e32 v16, v16, v126
	v_add_f32_e32 v17, v17, v126
	v_add_f32_e32 v18, v18, v126
	v_add_f32_e32 v19, v19, v126
	v_add_f32_e32 v12, v12, v126
	v_add_f32_e32 v13, v13, v126
	v_add_f32_e32 v14, v14, v126
	v_add_f32_e32 v15, v15, v126
	v_add_f32_e32 v8, v8, v126
	v_add_f32_e32 v9, v9, v126
	v_add_f32_e32 v10, v10, v126
	v_add_f32_e32 v11, v11, v126
	v_add_f32_e32 v4, v4, v126
	v_add_f32_e32 v5, v5, v126
	v_add_f32_e32 v6, v6, v126
	v_add_f32_e32 v7, v7, v126
	v_add_f32_e32 v0, v0, v126
	v_add_f32_e32 v1, v1, v126
	v_add_f32_e32 v2, v2, v126
	v_add_f32_e32 v3, v3, v126
	v_lshlrev_b32_e32 v30, 16, v28
	v_and_b32_e32 v28, 0xffff0000, v28
	v_lshlrev_b32_e32 v31, 16, v29
	v_and_b32_e32 v29, 0xffff0000, v29
	v_mul_f32_e32 v24, v24, v30
	v_mul_f32_e32 v25, v25, v28
	v_mul_f32_e32 v26, v26, v31
	v_mul_f32_e32 v27, v27, v29
	v_cvt_pk_bf16_f32 v24, v24, v25
	v_cvt_pk_bf16_f32 v25, v26, v27
	global_store_dwordx2 v[44:45], v[24:25], off offset:32
	v_mov_b32_e32 v24, v114
	v_mov_b32_e32 v25, v115
	v_lshlrev_b32_e32 v26, 16, v24
	v_and_b32_e32 v24, 0xffff0000, v24
	v_lshlrev_b32_e32 v27, 16, v25
	v_and_b32_e32 v25, 0xffff0000, v25
	v_mul_f32_e32 v20, v20, v26
	v_mul_f32_e32 v21, v21, v24
	v_mul_f32_e32 v22, v22, v27
	v_mul_f32_e32 v23, v23, v25
	v_cvt_pk_bf16_f32 v20, v20, v21
	v_cvt_pk_bf16_f32 v21, v22, v23
	global_store_dwordx2 v[44:45], v[20:21], off offset:64
	v_mov_b32_e32 v20, v116
	v_mov_b32_e32 v21, v117
	v_lshlrev_b32_e32 v22, 16, v20
	v_and_b32_e32 v20, 0xffff0000, v20
	v_lshlrev_b32_e32 v23, 16, v21
	v_and_b32_e32 v21, 0xffff0000, v21
	v_mul_f32_e32 v16, v16, v22
	v_mul_f32_e32 v17, v17, v20
	v_mul_f32_e32 v18, v18, v23
	v_mul_f32_e32 v19, v19, v21
	v_cvt_pk_bf16_f32 v16, v16, v17
	v_cvt_pk_bf16_f32 v17, v18, v19
	global_store_dwordx2 v[44:45], v[16:17], off offset:96
	v_mov_b32_e32 v16, v118
	v_mov_b32_e32 v17, v119
	v_lshlrev_b32_e32 v18, 16, v16
	v_and_b32_e32 v16, 0xffff0000, v16
	v_lshlrev_b32_e32 v19, 16, v17
	v_and_b32_e32 v17, 0xffff0000, v17
	v_mul_f32_e32 v12, v12, v18
	v_mul_f32_e32 v13, v13, v16
	v_mul_f32_e32 v14, v14, v19
	v_mul_f32_e32 v15, v15, v17
	v_cvt_pk_bf16_f32 v12, v12, v13
	v_cvt_pk_bf16_f32 v13, v14, v15
	global_store_dwordx2 v[44:45], v[12:13], off offset:128
	v_mov_b32_e32 v12, v120
	v_mov_b32_e32 v13, v121
	v_lshlrev_b32_e32 v14, 16, v12
	v_and_b32_e32 v12, 0xffff0000, v12
	v_lshlrev_b32_e32 v15, 16, v13
	v_and_b32_e32 v13, 0xffff0000, v13
	v_mul_f32_e32 v8, v8, v14
	v_mul_f32_e32 v9, v9, v12
	v_mul_f32_e32 v10, v10, v15
	v_mul_f32_e32 v11, v11, v13
	v_cvt_pk_bf16_f32 v8, v8, v9
	v_cvt_pk_bf16_f32 v9, v10, v11
	global_store_dwordx2 v[44:45], v[8:9], off offset:160
	v_mov_b32_e32 v8, v122
	v_mov_b32_e32 v9, v123
	v_lshlrev_b32_e32 v10, 16, v8
	v_and_b32_e32 v8, 0xffff0000, v8
	v_lshlrev_b32_e32 v11, 16, v9
	v_and_b32_e32 v9, 0xffff0000, v9
	v_mul_f32_e32 v4, v4, v10
	v_mul_f32_e32 v5, v5, v8
	v_mul_f32_e32 v6, v6, v11
	v_mul_f32_e32 v7, v7, v9
	v_cvt_pk_bf16_f32 v4, v4, v5
	v_cvt_pk_bf16_f32 v5, v6, v7
	global_store_dwordx2 v[44:45], v[4:5], off offset:192
	v_mov_b32_e32 v4, v124
	v_mov_b32_e32 v5, v125
	v_lshlrev_b32_e32 v6, 16, v4
	v_and_b32_e32 v4, 0xffff0000, v4
	v_lshlrev_b32_e32 v7, 16, v5
	v_and_b32_e32 v5, 0xffff0000, v5
	v_mul_f32_e32 v0, v0, v6
	v_mul_f32_e32 v1, v1, v4
	v_mul_f32_e32 v2, v2, v7
	v_mul_f32_e32 v3, v3, v5
	v_cvt_pk_bf16_f32 v0, v0, v1
	v_cvt_pk_bf16_f32 v1, v2, v3
	global_store_dwordx2 v[44:45], v[0:1], off offset:224
	s_cbranch_scc0 .LBB0_235

; __device__ __forceinline__ void attn_phase(LAS unsigned char* lds, const bf16_t* Q, const bf16_t* Kb, const bf16_t* VT, const bf16_t* Z, const float* kpart, bf16_t* Y, int G, int bid) {
;     ...
;     for (int pair = bid; pair < 256; pair += G) {
;         const int bh = pair >> 2, jp = pair & 3, b = bh >> 4, h = bh & 15;
.LBB0_639:
	s_and_b32 s8, s73, 7
	s_lshr_b32 s1, s73, 5
	s_lshl_b32 s1, s1, 3
	s_or_b32 s8, s8, s1
	s_lshl_b32 s8, s8, 2
	s_bfe_u32 s1, s73, 0x20003
	s_or_b32 s101, s8, s1
	s_lshl_b32 s8, s101, 5
	s_and_b32 s74, s101, 3
	s_ashr_i32 s1, s101, 6
	s_and_b32 s77, s8, 0x780
	s_xor_b32 s75, s74, 7
	s_lshl_b32 s0, s1, 11
	s_lshl_b32 s8, s77, 1
	s_add_u32 s10, s52, s8
	s_addc_u32 s11, s53, 0
	s_lshl_b32 s8, s77, 2
	v_lshl_add_u32 v0, s1, 4, v155
	s_add_u32 s8, s3, s8
	v_ashrrev_i32_e32 v1, 31, v0
	s_addc_u32 s9, s76, 0
	v_lshlrev_b64 v[0:1], 13, v[0:1]
	s_ashr_i32 s1, s0, 31
	v_lshl_add_u64 v[0:1], s[8:9], 0, v[0:1]
	s_lshl_b64 s[8:9], s[0:1], 12
	s_add_u32 s8, s10, s8
	v_or_b32_e32 v179, s0, v153
	s_addc_u32 s9, s11, s9
	s_or_b32 s0, s0, s77
	s_ashr_i32 s1, s0, 31
	v_lshl_add_u64 v[190:191], v[0:1], 0, v[184:185]
	s_lshl_b64 s[0:1], s[0:1], 12
	v_lshl_add_u64 v[192:193], s[8:9], 0, v[186:187]
	v_lshl_add_u64 v[194:195], v[150:151], 0, s[0:1]
	v_lshl_add_u64 v[196:197], v[190:191], 0, s[44:45]
	v_lshl_add_u64 v[198:199], v[190:191], 0, s[50:51]
	v_lshl_add_u64 v[200:201], v[190:191], 0, s[56:57]
	v_lshl_add_u64 v[202:203], v[190:191], 0, s[58:59]
	v_lshl_add_u64 v[204:205], v[190:191], 0, s[60:61]
	v_lshl_add_u64 v[206:207], v[190:191], 0, s[62:63]
	v_lshl_add_u64 v[208:209], v[190:191], 0, s[64:65]
	v_lshl_add_u64 v[210:211], v[190:191], 0, s[66:67]
	s_mov_b64 s[70:71], -1
	s_branch .LBB0_641

; #define LAS __attribute__((address_space(3)))
; __global__ void __launch_bounds__(NTHREADS, 2) mk_fwd(Params P) {
;     extern __shared__ __attribute__((aligned(16))) unsigned char lds_raw[];
;     LAS unsigned char* lds = (LAS unsigned char*)lds_raw;
;     cg::grid_group grid = cg::this_grid();
;     const int G = gridDim.x, bid = blockIdx.x, lo = P.lo, hi = P.hi;
	.amdhsa_kernel _Z6mk_fwd6Params
		.amdhsa_group_segment_fixed_size 0
		.amdhsa_private_segment_fixed_size 0
		.amdhsa_kernarg_size 384
		.amdhsa_user_sgpr_count 2
		.amdhsa_user_sgpr_dispatch_ptr 0
		.amdhsa_user_sgpr_queue_ptr 0
		.amdhsa_user_sgpr_kernarg_segment_ptr 1
		.amdhsa_user_sgpr_dispatch_id 0
		.amdhsa_user_sgpr_kernarg_preload_length 0
		.amdhsa_user_sgpr_kernarg_preload_offset 0
		.amdhsa_user_sgpr_private_segment_size 0
		.amdhsa_uses_dynamic_stack 0
		.amdhsa_enable_private_segment 0
		.amdhsa_system_sgpr_workgroup_id_x 1
		.amdhsa_system_sgpr_workgroup_id_y 0
		.amdhsa_system_sgpr_workgroup_id_z 0
		.amdhsa_system_sgpr_workgroup_info 0
		.amdhsa_system_vgpr_workitem_id 2
		.amdhsa_next_free_vgpr 250
		.amdhsa_next_free_sgpr 102
		.amdhsa_accum_offset 252
		.amdhsa_reserve_vcc 1
		.amdhsa_float_round_mode_32 0
		.amdhsa_float_round_mode_16_64 0
		.amdhsa_float_denorm_mode_32 3
		.amdhsa_float_denorm_mode_16_64 3
		.amdhsa_dx10_clamp 1
		.amdhsa_ieee_mode 1
		.amdhsa_fp16_overflow 0
		.amdhsa_tg_split 0
		.amdhsa_exception_fp_ieee_invalid_op 0
		.amdhsa_exception_fp_denorm_src 0
		.amdhsa_exception_fp_ieee_div_zero 0
		.amdhsa_exception_fp_ieee_overflow 0
		.amdhsa_exception_fp_ieee_underflow 0
		.amdhsa_exception_fp_ieee_inexact 0
		.amdhsa_exception_int_div_zero 0
	.end_amdhsa_kernel

; #define LAS __attribute__((address_space(3)))
; __global__ void __launch_bounds__(NTHREADS, 2) mk_fwd(Params P) {
;     extern __shared__ __attribute__((aligned(16))) unsigned char lds_raw[];
;     LAS unsigned char* lds = (LAS unsigned char*)lds_raw;
;     cg::grid_group grid = cg::this_grid();
;     const int G = gridDim.x, bid = blockIdx.x, lo = P.lo, hi = P.hi;
amdhsa.kernels:
  - .agpr_count:     0
    .args:
      - .offset:         0
        .size:           128
        .value_kind:     by_value
      - .offset:         128
        .size:           4
        .value_kind:     hidden_block_count_x
      - .offset:         132
        .size:           4
        .value_kind:     hidden_block_count_y
      - .offset:         136
        .size:           4
        .value_kind:     hidden_block_count_z
      - .offset:         140
        .size:           2
        .value_kind:     hidden_group_size_x
      - .offset:         142
        .size:           2
        .value_kind:     hidden_group_size_y
      - .offset:         144
        .size:           2
        .value_kind:     hidden_group_size_z
      - .offset:         146
        .size:           2
        .value_kind:     hidden_remainder_x
      - .offset:         148
        .size:           2
        .value_kind:     hidden_remainder_y
      - .offset:         150
        .size:           2
        .value_kind:     hidden_remainder_z
      - .offset:         168
        .size:           8
        .value_kind:     hidden_global_offset_x
      - .offset:         176
        .size:           8
        .value_kind:     hidden_global_offset_y
      - .offset:         184
        .size:           8
        .value_kind:     hidden_global_offset_z
      - .offset:         192
        .size:           2
        .value_kind:     hidden_grid_dims
      - .offset:         216
        .size:           8
        .value_kind:     hidden_multigrid_sync_arg
      - .offset:         248
        .size:           4
        .value_kind:     hidden_dynamic_lds_size
    .group_segment_fixed_size: 0
    .kernarg_segment_align: 8
    .kernarg_segment_size: 384
    .language:       OpenCL C
    .language_version:
      - 2
      - 0
    .max_flat_workgroup_size: 512
    .name:           _Z6mk_fwd6Params
    .private_segment_fixed_size: 0
    .sgpr_count:     108
    .sgpr_spill_count: 0
    .symbol:         _Z6mk_fwd6Params.kd
    .uniform_work_group_size: 1
    .uses_dynamic_stack: false
    .vgpr_count:     250
    .vgpr_spill_count: 0
    .wavefront_size: 64
